# static priority: waves 4-7 raised to prio 1 for the whole K-loop, per-block setprio flips deleted
# speedup vs baseline: 1.0108x; 1.0058x over previous
.LBB0_168:
	s_ashr_i32 s43, s42, 31
	s_lshl_b64 s[36:37], s[42:43], 20
	s_add_u32 s44, s20, s36
	s_addc_u32 s45, s21, s37
	s_and_b64 s[36:37], s[38:39], exec
	s_cselect_b32 s36, s45, s51
	s_cselect_b32 s37, s44, s50
	s_ashr_i32 s41, s40, 31
	s_lshl_b64 s[46:47], s[40:41], 15
	s_add_u32 s46, s33, s46
	s_addc_u32 s47, s56, s47
	s_and_b64 s[54:55], s[38:39], exec
	s_cselect_b32 s41, s47, s35
	s_cselect_b32 s43, s46, s34
	s_add_u32 s71, s34, 0x2c0000
	s_addc_u32 s76, s35, 0
	s_add_u32 s50, s50, 0x80080
	v_mov_b32_e32 v4, 0
	s_addc_u32 s51, s51, 0
	s_mov_b32 s77, -2
	v_mov_b32_e32 v5, v4
	v_mov_b32_e32 v6, v4
	v_mov_b32_e32 v7, v4
	v_mov_b32_e32 v8, v4
	v_mov_b32_e32 v9, v4
	v_mov_b32_e32 v10, v4
	v_mov_b32_e32 v11, v4
	v_mov_b32_e32 v20, v4
	v_mov_b32_e32 v21, v4
	v_mov_b32_e32 v22, v4
	v_mov_b32_e32 v23, v4
	v_mov_b32_e32 v24, v4
	v_mov_b32_e32 v25, v4
	v_mov_b32_e32 v26, v4
	v_mov_b32_e32 v27, v4
	v_mov_b32_e32 v36, v4
	v_mov_b32_e32 v37, v4
	v_mov_b32_e32 v38, v4
	v_mov_b32_e32 v39, v4
	v_mov_b32_e32 v40, v4
	v_mov_b32_e32 v41, v4
	v_mov_b32_e32 v42, v4
	v_mov_b32_e32 v43, v4
	v_mov_b32_e32 v52, v4
	v_mov_b32_e32 v53, v4
	v_mov_b32_e32 v54, v4
	v_mov_b32_e32 v55, v4
	v_mov_b32_e32 v56, v4
	v_mov_b32_e32 v57, v4
	v_mov_b32_e32 v58, v4
	v_mov_b32_e32 v59, v4
	v_mov_b32_e32 v12, v4
	v_mov_b32_e32 v13, v4
	v_mov_b32_e32 v14, v4
	v_mov_b32_e32 v15, v4
	v_mov_b32_e32 v16, v4
	v_mov_b32_e32 v17, v4
	v_mov_b32_e32 v18, v4
	v_mov_b32_e32 v19, v4
	v_mov_b32_e32 v28, v4
	v_mov_b32_e32 v29, v4
	v_mov_b32_e32 v30, v4
	v_mov_b32_e32 v31, v4
	v_mov_b32_e32 v32, v4
	v_mov_b32_e32 v33, v4
	v_mov_b32_e32 v34, v4
	v_mov_b32_e32 v35, v4
	v_mov_b32_e32 v44, v4
	v_mov_b32_e32 v45, v4
	v_mov_b32_e32 v46, v4
	v_mov_b32_e32 v47, v4
	v_mov_b32_e32 v48, v4
	v_mov_b32_e32 v49, v4
	v_mov_b32_e32 v50, v4
	v_mov_b32_e32 v51, v4
	v_mov_b32_e32 v60, v4
	v_mov_b32_e32 v61, v4
	v_mov_b32_e32 v62, v4
	v_mov_b32_e32 v63, v4
	v_mov_b32_e32 v64, v4
	v_mov_b32_e32 v65, v4
	v_mov_b32_e32 v66, v4
	v_mov_b32_e32 v67, v4
	v_mov_b32_e32 v68, v4
	v_mov_b32_e32 v69, v4
	v_mov_b32_e32 v70, v4
	v_mov_b32_e32 v71, v4
	v_mov_b32_e32 v72, v4
	v_mov_b32_e32 v73, v4
	v_mov_b32_e32 v74, v4
	v_mov_b32_e32 v75, v4
	v_mov_b32_e32 v84, v4
	v_mov_b32_e32 v85, v4
	v_mov_b32_e32 v86, v4
	v_mov_b32_e32 v87, v4
	v_mov_b32_e32 v88, v4
	v_mov_b32_e32 v89, v4
	v_mov_b32_e32 v90, v4
	v_mov_b32_e32 v91, v4
	v_mov_b32_e32 v100, v4
	v_mov_b32_e32 v101, v4
	v_mov_b32_e32 v102, v4
	v_mov_b32_e32 v103, v4
	v_mov_b32_e32 v104, v4
	v_mov_b32_e32 v105, v4
	v_mov_b32_e32 v106, v4
	v_mov_b32_e32 v107, v4
	v_mov_b32_e32 v116, v4
	v_mov_b32_e32 v117, v4
	v_mov_b32_e32 v118, v4
	v_mov_b32_e32 v119, v4
	v_mov_b32_e32 v120, v4
	v_mov_b32_e32 v121, v4
	v_mov_b32_e32 v122, v4
	v_mov_b32_e32 v123, v4
	v_mov_b32_e32 v76, v4
	v_mov_b32_e32 v77, v4
	v_mov_b32_e32 v78, v4
	v_mov_b32_e32 v79, v4
	v_mov_b32_e32 v80, v4
	v_mov_b32_e32 v81, v4
	v_mov_b32_e32 v82, v4
	v_mov_b32_e32 v83, v4
	v_mov_b32_e32 v92, v4
	v_mov_b32_e32 v93, v4
	v_mov_b32_e32 v94, v4
	v_mov_b32_e32 v95, v4
	v_mov_b32_e32 v96, v4
	v_mov_b32_e32 v97, v4
	v_mov_b32_e32 v98, v4
	v_mov_b32_e32 v99, v4
	v_mov_b32_e32 v108, v4
	v_mov_b32_e32 v109, v4
	v_mov_b32_e32 v110, v4
	v_mov_b32_e32 v111, v4
	v_mov_b32_e32 v112, v4
	v_mov_b32_e32 v113, v4
	v_mov_b32_e32 v114, v4
	v_mov_b32_e32 v115, v4
	v_mov_b32_e32 v124, v4
	v_mov_b32_e32 v125, v4
	v_mov_b32_e32 v126, v4
	v_mov_b32_e32 v127, v4
	v_mov_b32_e32 v128, v4
	v_mov_b32_e32 v129, v4
	v_mov_b32_e32 v130, v4
	v_mov_b32_e32 v131, v4
	v_readfirstlane_b32 s101, v156
	s_bitcmp1_b32 s101, 8
	s_cbranch_scc0 .Lprio_skip_1
	s_setprio 1
.Lprio_skip_1:
.LBB0_169:
	s_add_u32 s34, s50, 0xfff80080
	s_addc_u32 s35, s51, -1
	s_add_i32 s52, 0, 0x10000
	s_cmp_eq_u32 s77, 28
	s_cselect_b32 s55, s36, s35
	s_cselect_b32 s54, s37, s34
	v_add_u32_e32 v145, s52, v142
	s_cselect_b32 s35, s41, s76
	s_cselect_b32 s34, s43, s71
	s_add_i32 s53, 0, 0x14000
	ds_read_b128 v[146:149], v145
	ds_read_b128 v[150:153], v145 offset:1024
	ds_read_b128 v[172:175], v145 offset:2048
	ds_read_b128 v[176:179], v145 offset:3072
	v_add_u32_e32 v145, s53, v142
	ds_read_b128 v[180:183], v145
	ds_read_b128 v[184:187], v145 offset:1024
	ds_read_b128 v[188:191], v145 offset:2048
	ds_read_b128 v[192:195], v145 offset:3072
	v_lshl_add_u64 v[154:155], s[50:51], 0, v[138:139]
	s_add_i32 m0, s57, 0xc000
	ds_read_b128 v[196:199], v144
	ds_read_b128 v[200:203], v144 offset:1024
	ds_read_b128 v[204:207], v144 offset:2048
	ds_read_b128 v[208:211], v144 offset:3072
	ds_read_b128 v[212:215], v144 offset:4096
	ds_read_b128 v[216:219], v144 offset:5120
	ds_read_b128 v[228:231], v144 offset:6144
	ds_read_b128 v[232:235], v144 offset:7168
	global_load_lds_dwordx4 v[154:155], off
	v_lshl_add_u64 v[154:155], s[50:51], 0, v[140:141]
	s_add_i32 m0, s57, 0xe000
	s_nop 0
	global_load_lds_dwordx4 v[154:155], off
	s_waitcnt vmcnt(8)
	s_waitcnt lgkmcnt(0)
	s_barrier
	v_mfma_f32_16x16x32_bf16 v[128:131], v[146:149], v[196:199], v[128:131]
	v_mfma_f32_16x16x32_bf16 v[128:131], v[150:153], v[200:203], v[128:131]
	v_mfma_f32_16x16x32_bf16 v[124:127], v[172:175], v[196:199], v[124:127]
	v_mfma_f32_16x16x32_bf16 v[124:127], v[176:179], v[200:203], v[124:127]
	v_mfma_f32_16x16x32_bf16 v[108:111], v[172:175], v[204:207], v[108:111]
	v_mfma_f32_16x16x32_bf16 v[108:111], v[176:179], v[208:211], v[108:111]
	v_mfma_f32_16x16x32_bf16 v[112:115], v[146:149], v[204:207], v[112:115]
	v_mfma_f32_16x16x32_bf16 v[112:115], v[150:153], v[208:211], v[112:115]
	v_mfma_f32_16x16x32_bf16 v[96:99], v[146:149], v[212:215], v[96:99]
	v_mfma_f32_16x16x32_bf16 v[96:99], v[150:153], v[216:219], v[96:99]
	v_mfma_f32_16x16x32_bf16 v[92:95], v[172:175], v[212:215], v[92:95]
	v_mfma_f32_16x16x32_bf16 v[92:95], v[176:179], v[216:219], v[92:95]
	v_mfma_f32_16x16x32_bf16 v[76:79], v[172:175], v[228:231], v[76:79]
	v_mfma_f32_16x16x32_bf16 v[76:79], v[176:179], v[232:235], v[76:79]
	v_mfma_f32_16x16x32_bf16 v[80:83], v[146:149], v[228:231], v[80:83]
	v_mfma_f32_16x16x32_bf16 v[80:83], v[150:153], v[232:235], v[80:83]
	v_mfma_f32_16x16x32_bf16 v[120:123], v[180:183], v[196:199], v[120:123]
	v_mfma_f32_16x16x32_bf16 v[120:123], v[184:187], v[200:203], v[120:123]
	v_mfma_f32_16x16x32_bf16 v[116:119], v[188:191], v[196:199], v[116:119]
	v_mfma_f32_16x16x32_bf16 v[116:119], v[192:195], v[200:203], v[116:119]
	v_mfma_f32_16x16x32_bf16 v[100:103], v[188:191], v[204:207], v[100:103]
	v_mfma_f32_16x16x32_bf16 v[100:103], v[192:195], v[208:211], v[100:103]
	v_mfma_f32_16x16x32_bf16 v[104:107], v[180:183], v[204:207], v[104:107]
	v_mfma_f32_16x16x32_bf16 v[104:107], v[184:187], v[208:211], v[104:107]
	v_mfma_f32_16x16x32_bf16 v[88:91], v[180:183], v[212:215], v[88:91]
	v_mfma_f32_16x16x32_bf16 v[88:91], v[184:187], v[216:219], v[88:91]
	v_mfma_f32_16x16x32_bf16 v[84:87], v[188:191], v[212:215], v[84:87]
	v_mfma_f32_16x16x32_bf16 v[84:87], v[192:195], v[216:219], v[84:87]
	v_mfma_f32_16x16x32_bf16 v[68:71], v[188:191], v[228:231], v[68:71]
	v_mfma_f32_16x16x32_bf16 v[68:71], v[192:195], v[232:235], v[68:71]
	v_mfma_f32_16x16x32_bf16 v[72:75], v[180:183], v[228:231], v[72:75]
	v_mfma_f32_16x16x32_bf16 v[72:75], v[184:187], v[232:235], v[72:75]
	s_barrier
	s_add_i32 s52, s52, s19
	v_lshl_add_u64 v[154:155], s[34:35], 0, v[134:135]
	s_mov_b32 m0, s52
	ds_read_b128 v[196:199], v144 offset:16384
	ds_read_b128 v[200:203], v144 offset:17408
	ds_read_b128 v[204:207], v144 offset:18432
	ds_read_b128 v[208:211], v144 offset:19456
	ds_read_b128 v[212:215], v144 offset:20480
	ds_read_b128 v[216:219], v144 offset:21504
	ds_read_b128 v[228:231], v144 offset:22528
	ds_read_b128 v[232:235], v144 offset:23552
	global_load_lds_dwordx4 v[154:155], off
	s_add_i32 m0, s52, 0x2000
	s_add_u32 s96, s34, 0x4000
	v_lshl_add_u64 v[154:155], s[34:35], 0, v[0:1]
	s_addc_u32 s97, s35, 0
	s_add_i32 s52, s53, s19
	global_load_lds_dwordx4 v[154:155], off
	v_lshl_add_u64 v[154:155], s[96:97], 0, v[134:135]
	s_mov_b32 m0, s52
	v_lshl_add_u64 v[236:237], s[54:55], 0, v[132:133]
	global_load_lds_dwordx4 v[154:155], off
	v_lshl_add_u64 v[154:155], s[96:97], 0, v[0:1]
	s_add_i32 m0, s52, 0x2000
	s_nop 0
	global_load_lds_dwordx4 v[154:155], off
	v_lshl_add_u64 v[154:155], s[54:55], 0, v[136:137]
	s_mov_b32 m0, s57
	s_nop 0
	global_load_lds_dwordx4 v[154:155], off
	s_mov_b32 m0, s58
	s_nop 0
	global_load_lds_dwordx4 v[236:237], off
	s_waitcnt vmcnt(8)
	s_waitcnt lgkmcnt(0)
	s_barrier
	v_mfma_f32_16x16x32_bf16 v[64:67], v[146:149], v[196:199], v[64:67]
	v_mfma_f32_16x16x32_bf16 v[64:67], v[150:153], v[200:203], v[64:67]
	v_mfma_f32_16x16x32_bf16 v[60:63], v[172:175], v[196:199], v[60:63]
	v_mfma_f32_16x16x32_bf16 v[60:63], v[176:179], v[200:203], v[60:63]
	v_mfma_f32_16x16x32_bf16 v[44:47], v[172:175], v[204:207], v[44:47]
	v_mfma_f32_16x16x32_bf16 v[44:47], v[176:179], v[208:211], v[44:47]
	v_mfma_f32_16x16x32_bf16 v[48:51], v[146:149], v[204:207], v[48:51]
	v_mfma_f32_16x16x32_bf16 v[48:51], v[150:153], v[208:211], v[48:51]
	v_mfma_f32_16x16x32_bf16 v[32:35], v[146:149], v[212:215], v[32:35]
	v_mfma_f32_16x16x32_bf16 v[32:35], v[150:153], v[216:219], v[32:35]
	v_mfma_f32_16x16x32_bf16 v[28:31], v[172:175], v[212:215], v[28:31]
	v_mfma_f32_16x16x32_bf16 v[28:31], v[176:179], v[216:219], v[28:31]
	v_mfma_f32_16x16x32_bf16 v[12:15], v[172:175], v[228:231], v[12:15]
	v_mfma_f32_16x16x32_bf16 v[12:15], v[176:179], v[232:235], v[12:15]
	v_mfma_f32_16x16x32_bf16 v[16:19], v[146:149], v[228:231], v[16:19]
	v_mfma_f32_16x16x32_bf16 v[16:19], v[150:153], v[232:235], v[16:19]
	v_mfma_f32_16x16x32_bf16 v[56:59], v[180:183], v[196:199], v[56:59]
	v_mfma_f32_16x16x32_bf16 v[56:59], v[184:187], v[200:203], v[56:59]
	v_mfma_f32_16x16x32_bf16 v[52:55], v[188:191], v[196:199], v[52:55]
	v_mfma_f32_16x16x32_bf16 v[52:55], v[192:195], v[200:203], v[52:55]
	v_mfma_f32_16x16x32_bf16 v[36:39], v[188:191], v[204:207], v[36:39]
	v_mfma_f32_16x16x32_bf16 v[36:39], v[192:195], v[208:211], v[36:39]
	v_mfma_f32_16x16x32_bf16 v[40:43], v[180:183], v[204:207], v[40:43]
	v_mfma_f32_16x16x32_bf16 v[40:43], v[184:187], v[208:211], v[40:43]
	v_mfma_f32_16x16x32_bf16 v[24:27], v[180:183], v[212:215], v[24:27]
	v_mfma_f32_16x16x32_bf16 v[24:27], v[184:187], v[216:219], v[24:27]
	v_mfma_f32_16x16x32_bf16 v[20:23], v[188:191], v[212:215], v[20:23]
	v_mfma_f32_16x16x32_bf16 v[20:23], v[192:195], v[216:219], v[20:23]
	v_mfma_f32_16x16x32_bf16 v[4:7], v[188:191], v[228:231], v[4:7]
	v_mfma_f32_16x16x32_bf16 v[4:7], v[192:195], v[232:235], v[4:7]
	v_mfma_f32_16x16x32_bf16 v[8:11], v[180:183], v[228:231], v[8:11]
	v_mfma_f32_16x16x32_bf16 v[8:11], v[184:187], v[232:235], v[8:11]
	s_barrier
	s_add_i32 s52, 0, 0x18000
	v_add_u32_e32 v145, s52, v142
	s_add_i32 s53, 0, 0x1c000
	ds_read_b128 v[146:149], v145
	ds_read_b128 v[150:153], v145 offset:1024
	ds_read_b128 v[172:175], v145 offset:2048
	ds_read_b128 v[176:179], v145 offset:3072
	v_add_u32_e32 v145, s53, v142
	ds_read_b128 v[180:183], v145
	ds_read_b128 v[184:187], v145 offset:1024
	ds_read_b128 v[188:191], v145 offset:2048
	ds_read_b128 v[192:195], v145 offset:3072
	s_add_u32 s54, s54, 0x80000
	s_addc_u32 s55, s55, 0
	s_mov_b32 m0, s59
	v_lshl_add_u64 v[238:239], s[54:55], 0, v[136:137]
	ds_read_b128 v[196:199], v144 offset:32768
	ds_read_b128 v[200:203], v144 offset:33792
	ds_read_b128 v[204:207], v144 offset:34816
	ds_read_b128 v[208:211], v144 offset:35840
	ds_read_b128 v[212:215], v144 offset:36864
	ds_read_b128 v[216:219], v144 offset:37888
	ds_read_b128 v[228:231], v144 offset:38912
	ds_read_b128 v[232:235], v144 offset:39936
	global_load_lds_dwordx4 v[238:239], off
	v_lshl_add_u64 v[238:239], s[54:55], 0, v[132:133]
	s_mov_b32 m0, s60
	s_nop 0
	global_load_lds_dwordx4 v[238:239], off
	s_waitcnt vmcnt(8)
	s_waitcnt lgkmcnt(0)
	s_barrier
	v_mfma_f32_16x16x32_bf16 v[128:131], v[146:149], v[196:199], v[128:131]
	v_mfma_f32_16x16x32_bf16 v[128:131], v[150:153], v[200:203], v[128:131]
	v_mfma_f32_16x16x32_bf16 v[124:127], v[172:175], v[196:199], v[124:127]
	v_mfma_f32_16x16x32_bf16 v[124:127], v[176:179], v[200:203], v[124:127]
	v_mfma_f32_16x16x32_bf16 v[108:111], v[172:175], v[204:207], v[108:111]
	v_mfma_f32_16x16x32_bf16 v[108:111], v[176:179], v[208:211], v[108:111]
	v_mfma_f32_16x16x32_bf16 v[112:115], v[146:149], v[204:207], v[112:115]
	v_mfma_f32_16x16x32_bf16 v[112:115], v[150:153], v[208:211], v[112:115]
	v_mfma_f32_16x16x32_bf16 v[96:99], v[146:149], v[212:215], v[96:99]
	v_mfma_f32_16x16x32_bf16 v[96:99], v[150:153], v[216:219], v[96:99]
	v_mfma_f32_16x16x32_bf16 v[92:95], v[172:175], v[212:215], v[92:95]
	v_mfma_f32_16x16x32_bf16 v[92:95], v[176:179], v[216:219], v[92:95]
	v_mfma_f32_16x16x32_bf16 v[76:79], v[172:175], v[228:231], v[76:79]
	v_mfma_f32_16x16x32_bf16 v[76:79], v[176:179], v[232:235], v[76:79]
	v_mfma_f32_16x16x32_bf16 v[80:83], v[146:149], v[228:231], v[80:83]
	v_mfma_f32_16x16x32_bf16 v[80:83], v[150:153], v[232:235], v[80:83]
	v_mfma_f32_16x16x32_bf16 v[120:123], v[180:183], v[196:199], v[120:123]
	v_mfma_f32_16x16x32_bf16 v[120:123], v[184:187], v[200:203], v[120:123]
	v_mfma_f32_16x16x32_bf16 v[116:119], v[188:191], v[196:199], v[116:119]
	v_mfma_f32_16x16x32_bf16 v[116:119], v[192:195], v[200:203], v[116:119]
	v_mfma_f32_16x16x32_bf16 v[100:103], v[188:191], v[204:207], v[100:103]
	v_mfma_f32_16x16x32_bf16 v[100:103], v[192:195], v[208:211], v[100:103]
	v_mfma_f32_16x16x32_bf16 v[104:107], v[180:183], v[204:207], v[104:107]
	v_mfma_f32_16x16x32_bf16 v[104:107], v[184:187], v[208:211], v[104:107]
	v_mfma_f32_16x16x32_bf16 v[88:91], v[180:183], v[212:215], v[88:91]
	v_mfma_f32_16x16x32_bf16 v[88:91], v[184:187], v[216:219], v[88:91]
	v_mfma_f32_16x16x32_bf16 v[84:87], v[188:191], v[212:215], v[84:87]
	v_mfma_f32_16x16x32_bf16 v[84:87], v[192:195], v[216:219], v[84:87]
	v_mfma_f32_16x16x32_bf16 v[68:71], v[188:191], v[228:231], v[68:71]
	v_mfma_f32_16x16x32_bf16 v[68:71], v[192:195], v[232:235], v[68:71]
	v_mfma_f32_16x16x32_bf16 v[72:75], v[180:183], v[228:231], v[72:75]
	v_mfma_f32_16x16x32_bf16 v[72:75], v[184:187], v[232:235], v[72:75]
	s_barrier
	s_add_u32 s54, s34, 0x160000
	s_addc_u32 s55, s35, 0
	s_add_i32 s52, s52, s19
	v_lshl_add_u64 v[238:239], s[54:55], 0, v[134:135]
	s_mov_b32 m0, s52
	ds_read_b128 v[196:199], v144 offset:49152
	ds_read_b128 v[200:203], v144 offset:50176
	ds_read_b128 v[204:207], v144 offset:51200
	ds_read_b128 v[208:211], v144 offset:52224
	ds_read_b128 v[212:215], v144 offset:53248
	ds_read_b128 v[216:219], v144 offset:54272
	ds_read_b128 v[228:231], v144 offset:55296
	ds_read_b128 v[232:235], v144 offset:56320
	global_load_lds_dwordx4 v[238:239], off
	s_add_i32 m0, s52, 0x2000
	s_add_u32 s34, s34, 0x164000
	v_lshl_add_u64 v[238:239], s[54:55], 0, v[0:1]
	s_addc_u32 s35, s35, 0
	s_add_i32 s52, s53, s19
	global_load_lds_dwordx4 v[238:239], off
	v_lshl_add_u64 v[238:239], s[34:35], 0, v[134:135]
	s_mov_b32 m0, s52
	v_lshl_add_u64 v[154:155], v[154:155], 0, s[14:15]
	global_load_lds_dwordx4 v[238:239], off
	v_lshl_add_u64 v[238:239], s[34:35], 0, v[0:1]
	s_add_i32 m0, s52, 0x2000
	s_nop 0
	global_load_lds_dwordx4 v[238:239], off
	s_mov_b32 m0, s61
	s_nop 0
	global_load_lds_dwordx4 v[154:155], off
	v_lshl_add_u64 v[154:155], v[236:237], 0, s[14:15]
	s_mov_b32 m0, s62
	s_nop 0
	global_load_lds_dwordx4 v[154:155], off
	s_waitcnt vmcnt(8)
	s_waitcnt lgkmcnt(0)
	s_barrier
	v_mfma_f32_16x16x32_bf16 v[64:67], v[146:149], v[196:199], v[64:67]
	v_mfma_f32_16x16x32_bf16 v[64:67], v[150:153], v[200:203], v[64:67]
	v_mfma_f32_16x16x32_bf16 v[60:63], v[172:175], v[196:199], v[60:63]
	v_mfma_f32_16x16x32_bf16 v[60:63], v[176:179], v[200:203], v[60:63]
	v_mfma_f32_16x16x32_bf16 v[44:47], v[172:175], v[204:207], v[44:47]
	v_mfma_f32_16x16x32_bf16 v[44:47], v[176:179], v[208:211], v[44:47]
	v_mfma_f32_16x16x32_bf16 v[48:51], v[146:149], v[204:207], v[48:51]
	v_mfma_f32_16x16x32_bf16 v[48:51], v[150:153], v[208:211], v[48:51]
	v_mfma_f32_16x16x32_bf16 v[32:35], v[146:149], v[212:215], v[32:35]
	v_mfma_f32_16x16x32_bf16 v[32:35], v[150:153], v[216:219], v[32:35]
	v_mfma_f32_16x16x32_bf16 v[28:31], v[172:175], v[212:215], v[28:31]
	v_mfma_f32_16x16x32_bf16 v[28:31], v[176:179], v[216:219], v[28:31]
	v_mfma_f32_16x16x32_bf16 v[12:15], v[172:175], v[228:231], v[12:15]
	v_mfma_f32_16x16x32_bf16 v[12:15], v[176:179], v[232:235], v[12:15]
	v_mfma_f32_16x16x32_bf16 v[16:19], v[146:149], v[228:231], v[16:19]
	v_mfma_f32_16x16x32_bf16 v[16:19], v[150:153], v[232:235], v[16:19]
	v_mfma_f32_16x16x32_bf16 v[56:59], v[180:183], v[196:199], v[56:59]
	v_mfma_f32_16x16x32_bf16 v[56:59], v[184:187], v[200:203], v[56:59]
	v_mfma_f32_16x16x32_bf16 v[52:55], v[188:191], v[196:199], v[52:55]
	v_mfma_f32_16x16x32_bf16 v[52:55], v[192:195], v[200:203], v[52:55]
	v_mfma_f32_16x16x32_bf16 v[36:39], v[188:191], v[204:207], v[36:39]
	v_mfma_f32_16x16x32_bf16 v[36:39], v[192:195], v[208:211], v[36:39]
	v_mfma_f32_16x16x32_bf16 v[40:43], v[180:183], v[204:207], v[40:43]
	v_mfma_f32_16x16x32_bf16 v[40:43], v[184:187], v[208:211], v[40:43]
	v_mfma_f32_16x16x32_bf16 v[24:27], v[180:183], v[212:215], v[24:27]
	v_mfma_f32_16x16x32_bf16 v[24:27], v[184:187], v[216:219], v[24:27]
	v_mfma_f32_16x16x32_bf16 v[20:23], v[188:191], v[212:215], v[20:23]
	v_mfma_f32_16x16x32_bf16 v[20:23], v[192:195], v[216:219], v[20:23]
	v_mfma_f32_16x16x32_bf16 v[4:7], v[188:191], v[228:231], v[4:7]
	v_mfma_f32_16x16x32_bf16 v[4:7], v[192:195], v[232:235], v[4:7]
	v_mfma_f32_16x16x32_bf16 v[8:11], v[180:183], v[228:231], v[8:11]
	v_mfma_f32_16x16x32_bf16 v[8:11], v[184:187], v[232:235], v[8:11]
	s_barrier
	s_add_i32 s77, s77, 2
	s_add_u32 s71, s71, 0x2c0000
	s_addc_u32 s76, s76, 0
	s_add_u32 s50, s50, 0x100
	s_addc_u32 s51, s51, 0
	s_cmp_gt_u32 s77, 29
	s_cbranch_scc0 .LBB0_169
	s_setprio 0
	s_and_b64 vcc, exec, s[28:29]
	s_cbranch_vccz .LBB0_172
	s_barrier

.LBB0_242:
	s_ashr_i32 s57, s56, 31
	s_lshl_b64 s[36:37], s[56:57], 20
	s_add_u32 s58, s20, s36
	s_addc_u32 s59, s21, s37
	s_and_b64 s[36:37], s[42:43], exec
	s_cselect_b32 s36, s59, s45
	s_cselect_b32 s37, s58, s44
	s_ashr_i32 s55, s54, 31
	s_lshl_b64 s[46:47], s[54:55], 15
	s_add_u32 s60, s19, s46
	s_addc_u32 s61, s33, s47
	s_and_b64 s[46:47], s[42:43], exec
	s_cselect_b32 s55, s61, s35
	s_cselect_b32 s57, s60, s34
	s_add_u32 s63, s34, 0xe0000
	s_addc_u32 vcc_lo, s35, 0
	s_add_u32 s44, s44, 0x80080
	v_mov_b32_e32 v4, 0
	s_addc_u32 s45, s45, 0
	s_mov_b32 vcc_hi, -2
	v_mov_b32_e32 v5, v4
	v_mov_b32_e32 v6, v4
	v_mov_b32_e32 v7, v4
	v_mov_b32_e32 v8, v4
	v_mov_b32_e32 v9, v4
	v_mov_b32_e32 v10, v4
	v_mov_b32_e32 v11, v4
	v_mov_b32_e32 v20, v4
	v_mov_b32_e32 v21, v4
	v_mov_b32_e32 v22, v4
	v_mov_b32_e32 v23, v4
	v_mov_b32_e32 v24, v4
	v_mov_b32_e32 v25, v4
	v_mov_b32_e32 v26, v4
	v_mov_b32_e32 v27, v4
	v_mov_b32_e32 v36, v4
	v_mov_b32_e32 v37, v4
	s_waitcnt lgkmcnt(0)
	v_mov_b32_e32 v38, v4
	v_mov_b32_e32 v39, v4
	v_mov_b32_e32 v40, v4
	v_mov_b32_e32 v41, v4
	v_mov_b32_e32 v42, v4
	v_mov_b32_e32 v43, v4
	v_mov_b32_e32 v52, v4
	v_mov_b32_e32 v53, v4
	v_mov_b32_e32 v54, v4
	v_mov_b32_e32 v55, v4
	v_mov_b32_e32 v56, v4
	v_mov_b32_e32 v57, v4
	v_mov_b32_e32 v58, v4
	v_mov_b32_e32 v59, v4
	v_mov_b32_e32 v12, v4
	v_mov_b32_e32 v13, v4
	v_mov_b32_e32 v14, v4
	v_mov_b32_e32 v15, v4
	v_mov_b32_e32 v16, v4
	v_mov_b32_e32 v17, v4
	v_mov_b32_e32 v18, v4
	v_mov_b32_e32 v19, v4
	v_mov_b32_e32 v28, v4
	v_mov_b32_e32 v29, v4
	v_mov_b32_e32 v30, v4
	v_mov_b32_e32 v31, v4
	v_mov_b32_e32 v32, v4
	v_mov_b32_e32 v33, v4
	v_mov_b32_e32 v34, v4
	v_mov_b32_e32 v35, v4
	v_mov_b32_e32 v44, v4
	v_mov_b32_e32 v45, v4
	v_mov_b32_e32 v46, v4
	v_mov_b32_e32 v47, v4
	v_mov_b32_e32 v48, v4
	v_mov_b32_e32 v49, v4
	v_mov_b32_e32 v50, v4
	v_mov_b32_e32 v51, v4
	v_mov_b32_e32 v60, v4
	v_mov_b32_e32 v61, v4
	v_mov_b32_e32 v62, v4
	v_mov_b32_e32 v63, v4
	v_mov_b32_e32 v64, v4
	v_mov_b32_e32 v65, v4
	v_mov_b32_e32 v66, v4
	v_mov_b32_e32 v67, v4
	v_mov_b32_e32 v68, v4
	v_mov_b32_e32 v69, v4
	v_mov_b32_e32 v70, v4
	v_mov_b32_e32 v71, v4
	v_mov_b32_e32 v72, v4
	v_mov_b32_e32 v73, v4
	v_mov_b32_e32 v74, v4
	v_mov_b32_e32 v75, v4
	v_mov_b32_e32 v84, v4
	v_mov_b32_e32 v85, v4
	v_mov_b32_e32 v86, v4
	v_mov_b32_e32 v87, v4
	v_mov_b32_e32 v88, v4
	v_mov_b32_e32 v89, v4
	v_mov_b32_e32 v90, v4
	v_mov_b32_e32 v91, v4
	v_mov_b32_e32 v100, v4
	v_mov_b32_e32 v101, v4
	v_mov_b32_e32 v102, v4
	v_mov_b32_e32 v103, v4
	v_mov_b32_e32 v104, v4
	v_mov_b32_e32 v105, v4
	v_mov_b32_e32 v106, v4
	v_mov_b32_e32 v107, v4
	v_mov_b32_e32 v116, v4
	v_mov_b32_e32 v117, v4
	v_mov_b32_e32 v118, v4
	v_mov_b32_e32 v119, v4
	v_mov_b32_e32 v120, v4
	v_mov_b32_e32 v121, v4
	v_mov_b32_e32 v122, v4
	v_mov_b32_e32 v123, v4
	v_mov_b32_e32 v76, v4
	v_mov_b32_e32 v77, v4
	v_mov_b32_e32 v78, v4
	v_mov_b32_e32 v79, v4
	v_mov_b32_e32 v80, v4
	v_mov_b32_e32 v81, v4
	v_mov_b32_e32 v82, v4
	v_mov_b32_e32 v83, v4
	v_mov_b32_e32 v92, v4
	v_mov_b32_e32 v93, v4
	v_mov_b32_e32 v94, v4
	v_mov_b32_e32 v95, v4
	v_mov_b32_e32 v96, v4
	v_mov_b32_e32 v97, v4
	v_mov_b32_e32 v98, v4
	v_mov_b32_e32 v99, v4
	v_mov_b32_e32 v108, v4
	v_mov_b32_e32 v109, v4
	v_mov_b32_e32 v110, v4
	v_mov_b32_e32 v111, v4
	v_mov_b32_e32 v112, v4
	v_mov_b32_e32 v113, v4
	v_mov_b32_e32 v114, v4
	v_mov_b32_e32 v115, v4
	v_mov_b32_e32 v124, v4
	v_mov_b32_e32 v125, v4
	v_mov_b32_e32 v126, v4
	v_mov_b32_e32 v127, v4
	v_mov_b32_e32 v128, v4
	v_mov_b32_e32 v129, v4
	v_mov_b32_e32 v130, v4
	v_mov_b32_e32 v131, v4
	v_readfirstlane_b32 s101, v156
	s_bitcmp1_b32 s101, 8
	s_cbranch_scc0 .Lprio_skip_2
	s_setprio 1
.Lprio_skip_2:
.LBB0_243:
	s_add_u32 s34, s44, 0xfff80080
	s_addc_u32 s35, s45, -1
	s_add_i32 s52, 0, 0x10000
	s_cmp_eq_u32 vcc_hi, 28
	s_cselect_b32 s47, s36, s35
	s_cselect_b32 s46, s37, s34
	s_cselect_b32 s35, s55, vcc_lo
	s_cselect_b32 s34, s57, s63
	s_add_i32 s68, 0, 0x14000
	v_add_u32_e32 v144, s52, v155
	v_add_u32_e32 v180, s68, v155
	ds_read_b128 v[132:135], v144
	ds_read_b128 v[136:139], v144 offset:1024
	ds_read_b128 v[140:143], v144 offset:2048
	ds_read_b128 v[144:147], v144 offset:3072
	ds_read_b128 v[176:179], v180
	ds_read_b128 v[182:185], v180 offset:1024
	ds_read_b128 v[186:189], v180 offset:2048
	ds_read_b128 v[190:193], v180 offset:3072
	v_lshl_add_u64 v[218:219], s[44:45], 0, v[172:173]
	s_add_i32 m0, s69, 0xc000
	ds_read_b128 v[194:197], v181
	ds_read_b128 v[198:201], v181 offset:1024
	ds_read_b128 v[202:205], v181 offset:2048
	ds_read_b128 v[206:209], v181 offset:3072
	ds_read_b128 v[210:213], v181 offset:4096
	ds_read_b128 v[214:217], v181 offset:5120
	ds_read_b128 v[228:231], v181 offset:6144
	ds_read_b128 v[232:235], v181 offset:7168
	global_load_lds_dwordx4 v[218:219], off
	v_lshl_add_u64 v[218:219], s[44:45], 0, v[174:175]
	s_add_i32 m0, s69, 0xe000
	s_nop 0
	global_load_lds_dwordx4 v[218:219], off
	s_waitcnt vmcnt(8)
	s_waitcnt lgkmcnt(0)
	s_barrier
	v_mfma_f32_16x16x32_bf16 v[128:131], v[132:135], v[194:197], v[128:131]
	v_mfma_f32_16x16x32_bf16 v[128:131], v[136:139], v[198:201], v[128:131]
	v_mfma_f32_16x16x32_bf16 v[124:127], v[140:143], v[194:197], v[124:127]
	v_mfma_f32_16x16x32_bf16 v[124:127], v[144:147], v[198:201], v[124:127]
	v_mfma_f32_16x16x32_bf16 v[108:111], v[140:143], v[202:205], v[108:111]
	v_mfma_f32_16x16x32_bf16 v[108:111], v[144:147], v[206:209], v[108:111]
	v_mfma_f32_16x16x32_bf16 v[112:115], v[132:135], v[202:205], v[112:115]
	v_mfma_f32_16x16x32_bf16 v[112:115], v[136:139], v[206:209], v[112:115]
	v_mfma_f32_16x16x32_bf16 v[96:99], v[132:135], v[210:213], v[96:99]
	v_mfma_f32_16x16x32_bf16 v[96:99], v[136:139], v[214:217], v[96:99]
	v_mfma_f32_16x16x32_bf16 v[92:95], v[140:143], v[210:213], v[92:95]
	v_mfma_f32_16x16x32_bf16 v[92:95], v[144:147], v[214:217], v[92:95]
	v_mfma_f32_16x16x32_bf16 v[76:79], v[140:143], v[228:231], v[76:79]
	v_mfma_f32_16x16x32_bf16 v[76:79], v[144:147], v[232:235], v[76:79]
	v_mfma_f32_16x16x32_bf16 v[80:83], v[132:135], v[228:231], v[80:83]
	v_mfma_f32_16x16x32_bf16 v[80:83], v[136:139], v[232:235], v[80:83]
	v_mfma_f32_16x16x32_bf16 v[120:123], v[176:179], v[194:197], v[120:123]
	v_mfma_f32_16x16x32_bf16 v[120:123], v[182:185], v[198:201], v[120:123]
	v_mfma_f32_16x16x32_bf16 v[116:119], v[186:189], v[194:197], v[116:119]
	v_mfma_f32_16x16x32_bf16 v[116:119], v[190:193], v[198:201], v[116:119]
	v_mfma_f32_16x16x32_bf16 v[100:103], v[186:189], v[202:205], v[100:103]
	v_mfma_f32_16x16x32_bf16 v[100:103], v[190:193], v[206:209], v[100:103]
	v_mfma_f32_16x16x32_bf16 v[104:107], v[176:179], v[202:205], v[104:107]
	v_mfma_f32_16x16x32_bf16 v[104:107], v[182:185], v[206:209], v[104:107]
	v_mfma_f32_16x16x32_bf16 v[88:91], v[176:179], v[210:213], v[88:91]
	v_mfma_f32_16x16x32_bf16 v[88:91], v[182:185], v[214:217], v[88:91]
	v_mfma_f32_16x16x32_bf16 v[84:87], v[186:189], v[210:213], v[84:87]
	v_mfma_f32_16x16x32_bf16 v[84:87], v[190:193], v[214:217], v[84:87]
	v_mfma_f32_16x16x32_bf16 v[68:71], v[186:189], v[228:231], v[68:71]
	v_mfma_f32_16x16x32_bf16 v[68:71], v[190:193], v[232:235], v[68:71]
	v_mfma_f32_16x16x32_bf16 v[72:75], v[176:179], v[228:231], v[72:75]
	v_mfma_f32_16x16x32_bf16 v[72:75], v[182:185], v[232:235], v[72:75]
	s_barrier
	s_add_i32 s52, s52, s2
	v_lshl_add_u64 v[218:219], s[34:35], 0, v[150:151]
	s_mov_b32 m0, s52
	ds_read_b128 v[194:197], v181 offset:16384
	ds_read_b128 v[198:201], v181 offset:17408
	ds_read_b128 v[202:205], v181 offset:18432
	ds_read_b128 v[206:209], v181 offset:19456
	ds_read_b128 v[210:213], v181 offset:20480
	ds_read_b128 v[214:217], v181 offset:21504
	ds_read_b128 v[228:231], v181 offset:22528
	ds_read_b128 v[232:235], v181 offset:23552
	global_load_lds_dwordx4 v[218:219], off
	s_add_i32 m0, s52, 0x2000
	s_add_u32 s52, s34, 0x4000
	v_lshl_add_u64 v[218:219], s[34:35], 0, v[0:1]
	s_addc_u32 s53, s35, 0
	s_add_i32 s68, s68, s2
	global_load_lds_dwordx4 v[218:219], off
	v_lshl_add_u64 v[218:219], s[52:53], 0, v[150:151]
	s_mov_b32 m0, s68
	v_lshl_add_u64 v[236:237], s[46:47], 0, v[148:149]
	global_load_lds_dwordx4 v[218:219], off
	v_lshl_add_u64 v[218:219], s[52:53], 0, v[0:1]
	s_add_i32 m0, s68, 0x2000
	s_nop 0
	global_load_lds_dwordx4 v[218:219], off
	v_lshl_add_u64 v[218:219], s[46:47], 0, v[152:153]
	s_mov_b32 m0, s69
	s_nop 0
	global_load_lds_dwordx4 v[218:219], off
	s_mov_b32 m0, s71
	s_nop 0
	global_load_lds_dwordx4 v[236:237], off
	s_waitcnt vmcnt(8)
	s_waitcnt lgkmcnt(0)
	s_barrier
	v_mfma_f32_16x16x32_bf16 v[64:67], v[132:135], v[194:197], v[64:67]
	v_mfma_f32_16x16x32_bf16 v[64:67], v[136:139], v[198:201], v[64:67]
	v_mfma_f32_16x16x32_bf16 v[60:63], v[140:143], v[194:197], v[60:63]
	v_mfma_f32_16x16x32_bf16 v[60:63], v[144:147], v[198:201], v[60:63]
	v_mfma_f32_16x16x32_bf16 v[44:47], v[140:143], v[202:205], v[44:47]
	v_mfma_f32_16x16x32_bf16 v[44:47], v[144:147], v[206:209], v[44:47]
	v_mfma_f32_16x16x32_bf16 v[48:51], v[132:135], v[202:205], v[48:51]
	v_mfma_f32_16x16x32_bf16 v[48:51], v[136:139], v[206:209], v[48:51]
	v_mfma_f32_16x16x32_bf16 v[32:35], v[132:135], v[210:213], v[32:35]
	v_mfma_f32_16x16x32_bf16 v[32:35], v[136:139], v[214:217], v[32:35]
	v_mfma_f32_16x16x32_bf16 v[28:31], v[140:143], v[210:213], v[28:31]
	v_mfma_f32_16x16x32_bf16 v[28:31], v[144:147], v[214:217], v[28:31]
	v_mfma_f32_16x16x32_bf16 v[12:15], v[140:143], v[228:231], v[12:15]
	v_mfma_f32_16x16x32_bf16 v[12:15], v[144:147], v[232:235], v[12:15]
	v_mfma_f32_16x16x32_bf16 v[16:19], v[132:135], v[228:231], v[16:19]
	v_mfma_f32_16x16x32_bf16 v[16:19], v[136:139], v[232:235], v[16:19]
	v_mfma_f32_16x16x32_bf16 v[56:59], v[176:179], v[194:197], v[56:59]
	v_mfma_f32_16x16x32_bf16 v[56:59], v[182:185], v[198:201], v[56:59]
	v_mfma_f32_16x16x32_bf16 v[52:55], v[186:189], v[194:197], v[52:55]
	v_mfma_f32_16x16x32_bf16 v[52:55], v[190:193], v[198:201], v[52:55]
	v_mfma_f32_16x16x32_bf16 v[36:39], v[186:189], v[202:205], v[36:39]
	v_mfma_f32_16x16x32_bf16 v[36:39], v[190:193], v[206:209], v[36:39]
	v_mfma_f32_16x16x32_bf16 v[40:43], v[176:179], v[202:205], v[40:43]
	v_mfma_f32_16x16x32_bf16 v[40:43], v[182:185], v[206:209], v[40:43]
	v_mfma_f32_16x16x32_bf16 v[24:27], v[176:179], v[210:213], v[24:27]
	v_mfma_f32_16x16x32_bf16 v[24:27], v[182:185], v[214:217], v[24:27]
	v_mfma_f32_16x16x32_bf16 v[20:23], v[186:189], v[210:213], v[20:23]
	v_mfma_f32_16x16x32_bf16 v[20:23], v[190:193], v[214:217], v[20:23]
	v_mfma_f32_16x16x32_bf16 v[4:7], v[186:189], v[228:231], v[4:7]
	v_mfma_f32_16x16x32_bf16 v[4:7], v[190:193], v[232:235], v[4:7]
	v_mfma_f32_16x16x32_bf16 v[8:11], v[176:179], v[228:231], v[8:11]
	v_mfma_f32_16x16x32_bf16 v[8:11], v[182:185], v[232:235], v[8:11]
	s_barrier
	s_add_i32 s52, 0, 0x18000
	s_add_i32 s53, 0, 0x1c000
	v_add_u32_e32 v144, s52, v155
	v_add_u32_e32 v180, s53, v155
	ds_read_b128 v[132:135], v144
	ds_read_b128 v[136:139], v144 offset:1024
	ds_read_b128 v[140:143], v144 offset:2048
	ds_read_b128 v[144:147], v144 offset:3072
	ds_read_b128 v[176:179], v180
	ds_read_b128 v[182:185], v180 offset:1024
	ds_read_b128 v[186:189], v180 offset:2048
	ds_read_b128 v[190:193], v180 offset:3072
	s_add_u32 s46, s46, 0x80000
	s_addc_u32 s47, s47, 0
	s_mov_b32 m0, s88
	v_lshl_add_u64 v[238:239], s[46:47], 0, v[152:153]
	ds_read_b128 v[194:197], v181 offset:32768
	ds_read_b128 v[198:201], v181 offset:33792
	ds_read_b128 v[202:205], v181 offset:34816
	ds_read_b128 v[206:209], v181 offset:35840
	ds_read_b128 v[210:213], v181 offset:36864
	ds_read_b128 v[214:217], v181 offset:37888
	ds_read_b128 v[228:231], v181 offset:38912
	ds_read_b128 v[232:235], v181 offset:39936
	global_load_lds_dwordx4 v[238:239], off
	v_lshl_add_u64 v[238:239], s[46:47], 0, v[148:149]
	s_mov_b32 m0, s96
	s_nop 0
	global_load_lds_dwordx4 v[238:239], off
	s_waitcnt vmcnt(8)
	s_waitcnt lgkmcnt(0)
	s_barrier
	v_mfma_f32_16x16x32_bf16 v[128:131], v[132:135], v[194:197], v[128:131]
	v_mfma_f32_16x16x32_bf16 v[128:131], v[136:139], v[198:201], v[128:131]
	v_mfma_f32_16x16x32_bf16 v[124:127], v[140:143], v[194:197], v[124:127]
	v_mfma_f32_16x16x32_bf16 v[124:127], v[144:147], v[198:201], v[124:127]
	v_mfma_f32_16x16x32_bf16 v[108:111], v[140:143], v[202:205], v[108:111]
	v_mfma_f32_16x16x32_bf16 v[108:111], v[144:147], v[206:209], v[108:111]
	v_mfma_f32_16x16x32_bf16 v[112:115], v[132:135], v[202:205], v[112:115]
	v_mfma_f32_16x16x32_bf16 v[112:115], v[136:139], v[206:209], v[112:115]
	v_mfma_f32_16x16x32_bf16 v[96:99], v[132:135], v[210:213], v[96:99]
	v_mfma_f32_16x16x32_bf16 v[96:99], v[136:139], v[214:217], v[96:99]
	v_mfma_f32_16x16x32_bf16 v[92:95], v[140:143], v[210:213], v[92:95]
	v_mfma_f32_16x16x32_bf16 v[92:95], v[144:147], v[214:217], v[92:95]
	v_mfma_f32_16x16x32_bf16 v[76:79], v[140:143], v[228:231], v[76:79]
	v_mfma_f32_16x16x32_bf16 v[76:79], v[144:147], v[232:235], v[76:79]
	v_mfma_f32_16x16x32_bf16 v[80:83], v[132:135], v[228:231], v[80:83]
	v_mfma_f32_16x16x32_bf16 v[80:83], v[136:139], v[232:235], v[80:83]
	v_mfma_f32_16x16x32_bf16 v[120:123], v[176:179], v[194:197], v[120:123]
	v_mfma_f32_16x16x32_bf16 v[120:123], v[182:185], v[198:201], v[120:123]
	v_mfma_f32_16x16x32_bf16 v[116:119], v[186:189], v[194:197], v[116:119]
	v_mfma_f32_16x16x32_bf16 v[116:119], v[190:193], v[198:201], v[116:119]
	v_mfma_f32_16x16x32_bf16 v[100:103], v[186:189], v[202:205], v[100:103]
	v_mfma_f32_16x16x32_bf16 v[100:103], v[190:193], v[206:209], v[100:103]
	v_mfma_f32_16x16x32_bf16 v[104:107], v[176:179], v[202:205], v[104:107]
	v_mfma_f32_16x16x32_bf16 v[104:107], v[182:185], v[206:209], v[104:107]
	v_mfma_f32_16x16x32_bf16 v[88:91], v[176:179], v[210:213], v[88:91]
	v_mfma_f32_16x16x32_bf16 v[88:91], v[182:185], v[214:217], v[88:91]
	v_mfma_f32_16x16x32_bf16 v[84:87], v[186:189], v[210:213], v[84:87]
	v_mfma_f32_16x16x32_bf16 v[84:87], v[190:193], v[214:217], v[84:87]
	v_mfma_f32_16x16x32_bf16 v[68:71], v[186:189], v[228:231], v[68:71]
	v_mfma_f32_16x16x32_bf16 v[68:71], v[190:193], v[232:235], v[68:71]
	v_mfma_f32_16x16x32_bf16 v[72:75], v[176:179], v[228:231], v[72:75]
	v_mfma_f32_16x16x32_bf16 v[72:75], v[182:185], v[232:235], v[72:75]
	s_barrier
	s_add_u32 s46, s34, 0x70000
	s_addc_u32 s47, s35, 0
	s_add_i32 s52, s52, s2
	v_lshl_add_u64 v[238:239], s[46:47], 0, v[150:151]
	s_mov_b32 m0, s52
	ds_read_b128 v[194:197], v181 offset:49152
	ds_read_b128 v[198:201], v181 offset:50176
	ds_read_b128 v[202:205], v181 offset:51200
	ds_read_b128 v[206:209], v181 offset:52224
	ds_read_b128 v[210:213], v181 offset:53248
	ds_read_b128 v[214:217], v181 offset:54272
	ds_read_b128 v[228:231], v181 offset:55296
	ds_read_b128 v[232:235], v181 offset:56320
	global_load_lds_dwordx4 v[238:239], off
	s_add_i32 m0, s52, 0x2000
	s_add_u32 s34, s34, 0x74000
	v_lshl_add_u64 v[238:239], s[46:47], 0, v[0:1]
	s_addc_u32 s35, s35, 0
	s_add_i32 s46, s53, s2
	global_load_lds_dwordx4 v[238:239], off
	v_lshl_add_u64 v[238:239], s[34:35], 0, v[150:151]
	s_mov_b32 m0, s46
	v_lshl_add_u64 v[218:219], v[218:219], 0, s[14:15]
	global_load_lds_dwordx4 v[238:239], off
	v_lshl_add_u64 v[238:239], s[34:35], 0, v[0:1]
	s_add_i32 m0, s46, 0x2000
	s_nop 0
	global_load_lds_dwordx4 v[238:239], off
	s_mov_b32 m0, s97
	s_nop 0
	global_load_lds_dwordx4 v[218:219], off
	v_lshl_add_u64 v[218:219], v[236:237], 0, s[14:15]
	s_mov_b32 m0, s76
	s_nop 0
	global_load_lds_dwordx4 v[218:219], off
	s_waitcnt vmcnt(8)
	s_waitcnt lgkmcnt(0)
	s_barrier
	v_mfma_f32_16x16x32_bf16 v[64:67], v[132:135], v[194:197], v[64:67]
	v_mfma_f32_16x16x32_bf16 v[64:67], v[136:139], v[198:201], v[64:67]
	v_mfma_f32_16x16x32_bf16 v[60:63], v[140:143], v[194:197], v[60:63]
	v_mfma_f32_16x16x32_bf16 v[60:63], v[144:147], v[198:201], v[60:63]
	v_mfma_f32_16x16x32_bf16 v[44:47], v[140:143], v[202:205], v[44:47]
	v_mfma_f32_16x16x32_bf16 v[44:47], v[144:147], v[206:209], v[44:47]
	v_mfma_f32_16x16x32_bf16 v[48:51], v[132:135], v[202:205], v[48:51]
	v_mfma_f32_16x16x32_bf16 v[48:51], v[136:139], v[206:209], v[48:51]
	v_mfma_f32_16x16x32_bf16 v[32:35], v[132:135], v[210:213], v[32:35]
	v_mfma_f32_16x16x32_bf16 v[32:35], v[136:139], v[214:217], v[32:35]
	v_mfma_f32_16x16x32_bf16 v[28:31], v[140:143], v[210:213], v[28:31]
	v_mfma_f32_16x16x32_bf16 v[28:31], v[144:147], v[214:217], v[28:31]
	v_mfma_f32_16x16x32_bf16 v[12:15], v[140:143], v[228:231], v[12:15]
	v_mfma_f32_16x16x32_bf16 v[12:15], v[144:147], v[232:235], v[12:15]
	v_mfma_f32_16x16x32_bf16 v[16:19], v[132:135], v[228:231], v[16:19]
	v_mfma_f32_16x16x32_bf16 v[16:19], v[136:139], v[232:235], v[16:19]
	v_mfma_f32_16x16x32_bf16 v[56:59], v[176:179], v[194:197], v[56:59]
	v_mfma_f32_16x16x32_bf16 v[56:59], v[182:185], v[198:201], v[56:59]
	v_mfma_f32_16x16x32_bf16 v[52:55], v[186:189], v[194:197], v[52:55]
	v_mfma_f32_16x16x32_bf16 v[52:55], v[190:193], v[198:201], v[52:55]
	v_mfma_f32_16x16x32_bf16 v[36:39], v[186:189], v[202:205], v[36:39]
	v_mfma_f32_16x16x32_bf16 v[36:39], v[190:193], v[206:209], v[36:39]
	v_mfma_f32_16x16x32_bf16 v[40:43], v[176:179], v[202:205], v[40:43]
	v_mfma_f32_16x16x32_bf16 v[40:43], v[182:185], v[206:209], v[40:43]
	v_mfma_f32_16x16x32_bf16 v[24:27], v[176:179], v[210:213], v[24:27]
	v_mfma_f32_16x16x32_bf16 v[24:27], v[182:185], v[214:217], v[24:27]
	v_mfma_f32_16x16x32_bf16 v[20:23], v[186:189], v[210:213], v[20:23]
	v_mfma_f32_16x16x32_bf16 v[20:23], v[190:193], v[214:217], v[20:23]
	v_mfma_f32_16x16x32_bf16 v[4:7], v[186:189], v[228:231], v[4:7]
	v_mfma_f32_16x16x32_bf16 v[4:7], v[190:193], v[232:235], v[4:7]
	v_mfma_f32_16x16x32_bf16 v[8:11], v[176:179], v[228:231], v[8:11]
	v_mfma_f32_16x16x32_bf16 v[8:11], v[182:185], v[232:235], v[8:11]
	s_barrier
	s_add_i32 vcc_hi, vcc_hi, 2
	s_add_u32 s63, s63, 0xe0000
	s_addc_u32 vcc_lo, vcc_lo, 0
	s_add_u32 s44, s44, 0x100
	s_addc_u32 s45, s45, 0
	s_cmp_gt_u32 vcc_hi, 29
	s_cbranch_scc0 .LBB0_243
	s_setprio 0
	s_and_b64 vcc, exec, s[28:29]
	s_cbranch_vccz .LBB0_246
	s_barrier

.LBB0_558:
	s_ashr_i32 s49, s48, 31
	s_lshl_b64 s[36:37], s[48:49], 15
	s_add_u32 s54, s2, s36
	s_addc_u32 s55, s19, s37
	s_and_b64 s[36:37], s[42:43], exec
	s_cselect_b32 s36, s55, s35
	s_cselect_b32 s37, s54, s34
	s_add_u32 s49, s34, 0x80000
	s_addc_u32 s97, s35, 0
	s_add_u32 s42, s56, 0x80
	v_mov_b32_e32 v4, 0
	s_addc_u32 s43, s57, 0
	s_mov_b32 s34, 0
	s_waitcnt lgkmcnt(0)
	v_mov_b32_e32 v5, v4
	v_mov_b32_e32 v6, v4
	v_mov_b32_e32 v7, v4
	v_mov_b32_e32 v8, v4
	v_mov_b32_e32 v9, v4
	v_mov_b32_e32 v10, v4
	v_mov_b32_e32 v11, v4
	v_mov_b32_e32 v20, v4
	v_mov_b32_e32 v21, v4
	v_mov_b32_e32 v22, v4
	v_mov_b32_e32 v23, v4
	v_mov_b32_e32 v24, v4
	v_mov_b32_e32 v25, v4
	v_mov_b32_e32 v26, v4
	v_mov_b32_e32 v27, v4
	v_mov_b32_e32 v36, v4
	v_mov_b32_e32 v37, v4
	v_mov_b32_e32 v38, v4
	v_mov_b32_e32 v39, v4
	v_mov_b32_e32 v40, v4
	v_mov_b32_e32 v41, v4
	v_mov_b32_e32 v42, v4
	v_mov_b32_e32 v43, v4
	v_mov_b32_e32 v52, v4
	v_mov_b32_e32 v53, v4
	v_mov_b32_e32 v54, v4
	v_mov_b32_e32 v55, v4
	v_mov_b32_e32 v56, v4
	v_mov_b32_e32 v57, v4
	v_mov_b32_e32 v58, v4
	v_mov_b32_e32 v59, v4
	v_mov_b32_e32 v12, v4
	v_mov_b32_e32 v13, v4
	v_mov_b32_e32 v14, v4
	v_mov_b32_e32 v15, v4
	v_mov_b32_e32 v16, v4
	v_mov_b32_e32 v17, v4
	v_mov_b32_e32 v18, v4
	v_mov_b32_e32 v19, v4
	v_mov_b32_e32 v28, v4
	v_mov_b32_e32 v29, v4
	v_mov_b32_e32 v30, v4
	v_mov_b32_e32 v31, v4
	v_mov_b32_e32 v32, v4
	v_mov_b32_e32 v33, v4
	v_mov_b32_e32 v34, v4
	v_mov_b32_e32 v35, v4
	v_mov_b32_e32 v44, v4
	v_mov_b32_e32 v45, v4
	v_mov_b32_e32 v46, v4
	v_mov_b32_e32 v47, v4
	v_mov_b32_e32 v48, v4
	v_mov_b32_e32 v49, v4
	v_mov_b32_e32 v50, v4
	v_mov_b32_e32 v51, v4
	v_mov_b32_e32 v60, v4
	v_mov_b32_e32 v61, v4
	v_mov_b32_e32 v62, v4
	v_mov_b32_e32 v63, v4
	v_mov_b32_e32 v64, v4
	v_mov_b32_e32 v65, v4
	v_mov_b32_e32 v66, v4
	v_mov_b32_e32 v67, v4
	v_mov_b32_e32 v68, v4
	v_mov_b32_e32 v69, v4
	v_mov_b32_e32 v70, v4
	v_mov_b32_e32 v71, v4
	v_mov_b32_e32 v72, v4
	v_mov_b32_e32 v73, v4
	v_mov_b32_e32 v74, v4
	v_mov_b32_e32 v75, v4
	v_mov_b32_e32 v84, v4
	v_mov_b32_e32 v85, v4
	v_mov_b32_e32 v86, v4
	v_mov_b32_e32 v87, v4
	v_mov_b32_e32 v88, v4
	v_mov_b32_e32 v89, v4
	v_mov_b32_e32 v90, v4
	v_mov_b32_e32 v91, v4
	v_mov_b32_e32 v100, v4
	v_mov_b32_e32 v101, v4
	v_mov_b32_e32 v102, v4
	v_mov_b32_e32 v103, v4
	v_mov_b32_e32 v104, v4
	v_mov_b32_e32 v105, v4
	v_mov_b32_e32 v106, v4
	v_mov_b32_e32 v107, v4
	v_mov_b32_e32 v128, v4
	v_mov_b32_e32 v129, v4
	v_mov_b32_e32 v130, v4
	v_mov_b32_e32 v131, v4
	v_mov_b32_e32 v132, v4
	v_mov_b32_e32 v133, v4
	v_mov_b32_e32 v134, v4
	v_mov_b32_e32 v135, v4
	v_mov_b32_e32 v76, v4
	v_mov_b32_e32 v77, v4
	v_mov_b32_e32 v78, v4
	v_mov_b32_e32 v79, v4
	v_mov_b32_e32 v80, v4
	v_mov_b32_e32 v81, v4
	v_mov_b32_e32 v82, v4
	v_mov_b32_e32 v83, v4
	v_mov_b32_e32 v92, v4
	v_mov_b32_e32 v93, v4
	v_mov_b32_e32 v94, v4
	v_mov_b32_e32 v95, v4
	v_mov_b32_e32 v96, v4
	v_mov_b32_e32 v97, v4
	v_mov_b32_e32 v98, v4
	v_mov_b32_e32 v99, v4
	v_mov_b32_e32 v108, v4
	v_mov_b32_e32 v109, v4
	v_mov_b32_e32 v110, v4
	v_mov_b32_e32 v111, v4
	v_mov_b32_e32 v112, v4
	v_mov_b32_e32 v113, v4
	v_mov_b32_e32 v114, v4
	v_mov_b32_e32 v115, v4
	v_mov_b32_e32 v140, v4
	v_mov_b32_e32 v141, v4
	v_mov_b32_e32 v142, v4
	v_mov_b32_e32 v143, v4
	v_mov_b32_e32 v144, v4
	v_mov_b32_e32 v145, v4
	v_mov_b32_e32 v146, v4
	v_mov_b32_e32 v147, v4
	v_readfirstlane_b32 s101, v156
	s_bitcmp1_b32 s101, 8
	s_cbranch_scc0 .Lprio_skip_3
	s_setprio 1
.Lprio_skip_3:
.LBB0_559:
	s_add_i32 vcc_lo, s34, 2
	s_add_u32 s35, s42, 0x80
	s_addc_u32 s52, s43, 0
	s_add_i32 s53, 0, 0x10000
	s_cmp_eq_u32 s77, s34
	s_cselect_b32 s57, s51, s52
	s_cselect_b32 s56, s50, s35
	s_cselect_b32 s35, s36, s97
	s_cselect_b32 s34, s37, s49
	s_add_i32 s68, 0, 0x14000
	v_add_u32_e32 v136, s53, v200
	v_add_u32_e32 v186, s68, v200
	ds_read_b128 v[116:119], v136
	ds_read_b128 v[120:123], v136 offset:1024
	ds_read_b128 v[124:127], v136 offset:2048
	ds_read_b128 v[136:139], v136 offset:3072
	ds_read_b128 v[148:151], v186
	ds_read_b128 v[152:155], v186 offset:1024
	ds_read_b128 v[182:185], v186 offset:2048
	ds_read_b128 v[186:189], v186 offset:3072
	v_lshl_add_u64 v[198:199], s[42:43], 0, v[178:179]
	s_add_i32 m0, s59, 0xc000
	ds_read_b128 v[190:193], v202
	ds_read_b128 v[194:197], v202 offset:1024
	ds_read_b128 v[204:207], v202 offset:2048
	ds_read_b128 v[208:211], v202 offset:3072
	ds_read_b128 v[212:215], v202 offset:4096
	ds_read_b128 v[216:219], v202 offset:5120
	ds_read_b128 v[228:231], v202 offset:6144
	ds_read_b128 v[232:235], v202 offset:7168
	global_load_lds_dwordx4 v[198:199], off
	v_lshl_add_u64 v[198:199], s[42:43], 0, v[180:181]
	s_add_i32 m0, s59, 0xe000
	s_nop 0
	global_load_lds_dwordx4 v[198:199], off
	s_waitcnt vmcnt(8)
	s_waitcnt lgkmcnt(0)
	s_barrier
	v_mfma_f32_16x16x32_bf16 v[144:147], v[116:119], v[190:193], v[144:147]
	v_mfma_f32_16x16x32_bf16 v[144:147], v[120:123], v[194:197], v[144:147]
	v_mfma_f32_16x16x32_bf16 v[140:143], v[124:127], v[190:193], v[140:143]
	v_mfma_f32_16x16x32_bf16 v[140:143], v[136:139], v[194:197], v[140:143]
	v_mfma_f32_16x16x32_bf16 v[108:111], v[124:127], v[204:207], v[108:111]
	v_mfma_f32_16x16x32_bf16 v[108:111], v[136:139], v[208:211], v[108:111]
	v_mfma_f32_16x16x32_bf16 v[112:115], v[116:119], v[204:207], v[112:115]
	v_mfma_f32_16x16x32_bf16 v[112:115], v[120:123], v[208:211], v[112:115]
	v_mfma_f32_16x16x32_bf16 v[96:99], v[116:119], v[212:215], v[96:99]
	v_mfma_f32_16x16x32_bf16 v[96:99], v[120:123], v[216:219], v[96:99]
	v_mfma_f32_16x16x32_bf16 v[92:95], v[124:127], v[212:215], v[92:95]
	v_mfma_f32_16x16x32_bf16 v[92:95], v[136:139], v[216:219], v[92:95]
	v_mfma_f32_16x16x32_bf16 v[76:79], v[124:127], v[228:231], v[76:79]
	v_mfma_f32_16x16x32_bf16 v[76:79], v[136:139], v[232:235], v[76:79]
	v_mfma_f32_16x16x32_bf16 v[80:83], v[116:119], v[228:231], v[80:83]
	v_mfma_f32_16x16x32_bf16 v[80:83], v[120:123], v[232:235], v[80:83]
	v_mfma_f32_16x16x32_bf16 v[132:135], v[148:151], v[190:193], v[132:135]
	v_mfma_f32_16x16x32_bf16 v[132:135], v[152:155], v[194:197], v[132:135]
	v_mfma_f32_16x16x32_bf16 v[128:131], v[182:185], v[190:193], v[128:131]
	v_mfma_f32_16x16x32_bf16 v[128:131], v[186:189], v[194:197], v[128:131]
	v_mfma_f32_16x16x32_bf16 v[100:103], v[182:185], v[204:207], v[100:103]
	v_mfma_f32_16x16x32_bf16 v[100:103], v[186:189], v[208:211], v[100:103]
	v_mfma_f32_16x16x32_bf16 v[104:107], v[148:151], v[204:207], v[104:107]
	v_mfma_f32_16x16x32_bf16 v[104:107], v[152:155], v[208:211], v[104:107]
	v_mfma_f32_16x16x32_bf16 v[88:91], v[148:151], v[212:215], v[88:91]
	v_mfma_f32_16x16x32_bf16 v[88:91], v[152:155], v[216:219], v[88:91]
	v_mfma_f32_16x16x32_bf16 v[84:87], v[182:185], v[212:215], v[84:87]
	v_mfma_f32_16x16x32_bf16 v[84:87], v[186:189], v[216:219], v[84:87]
	v_mfma_f32_16x16x32_bf16 v[68:71], v[182:185], v[228:231], v[68:71]
	v_mfma_f32_16x16x32_bf16 v[68:71], v[186:189], v[232:235], v[68:71]
	v_mfma_f32_16x16x32_bf16 v[72:75], v[148:151], v[228:231], v[72:75]
	v_mfma_f32_16x16x32_bf16 v[72:75], v[152:155], v[232:235], v[72:75]
	s_barrier
	s_add_i32 s52, s53, s58
	v_lshl_add_u64 v[198:199], s[34:35], 0, v[174:175]
	s_mov_b32 m0, s52
	ds_read_b128 v[190:193], v202 offset:16384
	ds_read_b128 v[194:197], v202 offset:17408
	ds_read_b128 v[204:207], v202 offset:18432
	ds_read_b128 v[208:211], v202 offset:19456
	ds_read_b128 v[212:215], v202 offset:20480
	ds_read_b128 v[216:219], v202 offset:21504
	ds_read_b128 v[228:231], v202 offset:22528
	ds_read_b128 v[232:235], v202 offset:23552
	global_load_lds_dwordx4 v[198:199], off
	s_add_i32 m0, s52, 0x2000
	s_add_u32 s52, s34, 0x4000
	v_lshl_add_u64 v[198:199], s[34:35], 0, v[0:1]
	s_addc_u32 s53, s35, 0
	s_add_i32 s68, s68, s58
	global_load_lds_dwordx4 v[198:199], off
	v_lshl_add_u64 v[198:199], s[52:53], 0, v[174:175]
	s_mov_b32 m0, s68
	v_lshl_add_u64 v[236:237], s[56:57], 0, v[172:173]
	global_load_lds_dwordx4 v[198:199], off
	v_lshl_add_u64 v[198:199], s[52:53], 0, v[0:1]
	s_add_i32 m0, s68, 0x2000
	s_nop 0
	global_load_lds_dwordx4 v[198:199], off
	v_lshl_add_u64 v[198:199], s[56:57], 0, v[176:177]
	s_mov_b32 m0, s59
	s_nop 0
	global_load_lds_dwordx4 v[198:199], off
	s_mov_b32 m0, s60
	s_nop 0
	global_load_lds_dwordx4 v[236:237], off
	s_waitcnt vmcnt(8)
	s_waitcnt lgkmcnt(0)
	s_barrier
	v_mfma_f32_16x16x32_bf16 v[64:67], v[116:119], v[190:193], v[64:67]
	v_mfma_f32_16x16x32_bf16 v[64:67], v[120:123], v[194:197], v[64:67]
	v_mfma_f32_16x16x32_bf16 v[60:63], v[124:127], v[190:193], v[60:63]
	v_mfma_f32_16x16x32_bf16 v[60:63], v[136:139], v[194:197], v[60:63]
	v_mfma_f32_16x16x32_bf16 v[44:47], v[124:127], v[204:207], v[44:47]
	v_mfma_f32_16x16x32_bf16 v[44:47], v[136:139], v[208:211], v[44:47]
	v_mfma_f32_16x16x32_bf16 v[48:51], v[116:119], v[204:207], v[48:51]
	v_mfma_f32_16x16x32_bf16 v[48:51], v[120:123], v[208:211], v[48:51]
	v_mfma_f32_16x16x32_bf16 v[32:35], v[116:119], v[212:215], v[32:35]
	v_mfma_f32_16x16x32_bf16 v[32:35], v[120:123], v[216:219], v[32:35]
	v_mfma_f32_16x16x32_bf16 v[28:31], v[124:127], v[212:215], v[28:31]
	v_mfma_f32_16x16x32_bf16 v[28:31], v[136:139], v[216:219], v[28:31]
	v_mfma_f32_16x16x32_bf16 v[12:15], v[124:127], v[228:231], v[12:15]
	v_mfma_f32_16x16x32_bf16 v[12:15], v[136:139], v[232:235], v[12:15]
	v_mfma_f32_16x16x32_bf16 v[16:19], v[116:119], v[228:231], v[16:19]
	v_mfma_f32_16x16x32_bf16 v[16:19], v[120:123], v[232:235], v[16:19]
	v_mfma_f32_16x16x32_bf16 v[56:59], v[148:151], v[190:193], v[56:59]
	v_mfma_f32_16x16x32_bf16 v[56:59], v[152:155], v[194:197], v[56:59]
	v_mfma_f32_16x16x32_bf16 v[52:55], v[182:185], v[190:193], v[52:55]
	v_mfma_f32_16x16x32_bf16 v[52:55], v[186:189], v[194:197], v[52:55]
	v_mfma_f32_16x16x32_bf16 v[36:39], v[182:185], v[204:207], v[36:39]
	v_mfma_f32_16x16x32_bf16 v[36:39], v[186:189], v[208:211], v[36:39]
	v_mfma_f32_16x16x32_bf16 v[40:43], v[148:151], v[204:207], v[40:43]
	v_mfma_f32_16x16x32_bf16 v[40:43], v[152:155], v[208:211], v[40:43]
	v_mfma_f32_16x16x32_bf16 v[24:27], v[148:151], v[212:215], v[24:27]
	v_mfma_f32_16x16x32_bf16 v[24:27], v[152:155], v[216:219], v[24:27]
	v_mfma_f32_16x16x32_bf16 v[20:23], v[182:185], v[212:215], v[20:23]
	v_mfma_f32_16x16x32_bf16 v[20:23], v[186:189], v[216:219], v[20:23]
	v_mfma_f32_16x16x32_bf16 v[4:7], v[182:185], v[228:231], v[4:7]
	v_mfma_f32_16x16x32_bf16 v[4:7], v[186:189], v[232:235], v[4:7]
	v_mfma_f32_16x16x32_bf16 v[8:11], v[148:151], v[228:231], v[8:11]
	v_mfma_f32_16x16x32_bf16 v[8:11], v[152:155], v[232:235], v[8:11]
	s_barrier
	s_add_i32 s68, 0, 0x18000
	s_add_i32 vcc_hi, 0, 0x1c000
	v_add_u32_e32 v136, s68, v200
	v_add_u32_e32 v186, vcc_hi, v200
	ds_read_b128 v[116:119], v136
	ds_read_b128 v[120:123], v136 offset:1024
	ds_read_b128 v[124:127], v136 offset:2048
	ds_read_b128 v[136:139], v136 offset:3072
	ds_read_b128 v[148:151], v186
	ds_read_b128 v[152:155], v186 offset:1024
	ds_read_b128 v[182:185], v186 offset:2048
	ds_read_b128 v[186:189], v186 offset:3072
	s_add_u32 s52, s56, s26
	s_addc_u32 s53, s57, 0
	s_mov_b32 m0, s61
	v_lshl_add_u64 v[238:239], s[52:53], 0, v[176:177]
	ds_read_b128 v[190:193], v202 offset:32768
	ds_read_b128 v[194:197], v202 offset:33792
	ds_read_b128 v[204:207], v202 offset:34816
	ds_read_b128 v[208:211], v202 offset:35840
	ds_read_b128 v[212:215], v202 offset:36864
	ds_read_b128 v[216:219], v202 offset:37888
	ds_read_b128 v[228:231], v202 offset:38912
	ds_read_b128 v[232:235], v202 offset:39936
	global_load_lds_dwordx4 v[238:239], off
	v_lshl_add_u64 v[238:239], s[52:53], 0, v[172:173]
	s_mov_b32 m0, s62
	s_nop 0
	global_load_lds_dwordx4 v[238:239], off
	s_waitcnt vmcnt(8)
	s_waitcnt lgkmcnt(0)
	s_barrier
	v_mfma_f32_16x16x32_bf16 v[144:147], v[116:119], v[190:193], v[144:147]
	v_mfma_f32_16x16x32_bf16 v[144:147], v[120:123], v[194:197], v[144:147]
	v_mfma_f32_16x16x32_bf16 v[140:143], v[124:127], v[190:193], v[140:143]
	v_mfma_f32_16x16x32_bf16 v[140:143], v[136:139], v[194:197], v[140:143]
	v_mfma_f32_16x16x32_bf16 v[108:111], v[124:127], v[204:207], v[108:111]
	v_mfma_f32_16x16x32_bf16 v[108:111], v[136:139], v[208:211], v[108:111]
	v_mfma_f32_16x16x32_bf16 v[112:115], v[116:119], v[204:207], v[112:115]
	v_mfma_f32_16x16x32_bf16 v[112:115], v[120:123], v[208:211], v[112:115]
	v_mfma_f32_16x16x32_bf16 v[96:99], v[116:119], v[212:215], v[96:99]
	v_mfma_f32_16x16x32_bf16 v[96:99], v[120:123], v[216:219], v[96:99]
	v_mfma_f32_16x16x32_bf16 v[92:95], v[124:127], v[212:215], v[92:95]
	v_mfma_f32_16x16x32_bf16 v[92:95], v[136:139], v[216:219], v[92:95]
	v_mfma_f32_16x16x32_bf16 v[76:79], v[124:127], v[228:231], v[76:79]
	v_mfma_f32_16x16x32_bf16 v[76:79], v[136:139], v[232:235], v[76:79]
	v_mfma_f32_16x16x32_bf16 v[80:83], v[116:119], v[228:231], v[80:83]
	v_mfma_f32_16x16x32_bf16 v[80:83], v[120:123], v[232:235], v[80:83]
	v_mfma_f32_16x16x32_bf16 v[132:135], v[148:151], v[190:193], v[132:135]
	v_mfma_f32_16x16x32_bf16 v[132:135], v[152:155], v[194:197], v[132:135]
	v_mfma_f32_16x16x32_bf16 v[128:131], v[182:185], v[190:193], v[128:131]
	v_mfma_f32_16x16x32_bf16 v[128:131], v[186:189], v[194:197], v[128:131]
	v_mfma_f32_16x16x32_bf16 v[100:103], v[182:185], v[204:207], v[100:103]
	v_mfma_f32_16x16x32_bf16 v[100:103], v[186:189], v[208:211], v[100:103]
	v_mfma_f32_16x16x32_bf16 v[104:107], v[148:151], v[204:207], v[104:107]
	v_mfma_f32_16x16x32_bf16 v[104:107], v[152:155], v[208:211], v[104:107]
	v_mfma_f32_16x16x32_bf16 v[88:91], v[148:151], v[212:215], v[88:91]
	v_mfma_f32_16x16x32_bf16 v[88:91], v[152:155], v[216:219], v[88:91]
	v_mfma_f32_16x16x32_bf16 v[84:87], v[182:185], v[212:215], v[84:87]
	v_mfma_f32_16x16x32_bf16 v[84:87], v[186:189], v[216:219], v[84:87]
	v_mfma_f32_16x16x32_bf16 v[68:71], v[182:185], v[228:231], v[68:71]
	v_mfma_f32_16x16x32_bf16 v[68:71], v[186:189], v[232:235], v[68:71]
	v_mfma_f32_16x16x32_bf16 v[72:75], v[148:151], v[228:231], v[72:75]
	v_mfma_f32_16x16x32_bf16 v[72:75], v[152:155], v[232:235], v[72:75]
	s_barrier
	s_add_u32 s52, s34, 0x40000
	s_addc_u32 s53, s35, 0
	s_add_i32 s56, s68, s58
	v_lshl_add_u64 v[238:239], s[52:53], 0, v[174:175]
	s_mov_b32 m0, s56
	ds_read_b128 v[190:193], v202 offset:49152
	ds_read_b128 v[194:197], v202 offset:50176
	ds_read_b128 v[204:207], v202 offset:51200
	ds_read_b128 v[208:211], v202 offset:52224
	ds_read_b128 v[212:215], v202 offset:53248
	ds_read_b128 v[216:219], v202 offset:54272
	ds_read_b128 v[228:231], v202 offset:55296
	ds_read_b128 v[232:235], v202 offset:56320
	global_load_lds_dwordx4 v[238:239], off
	s_add_i32 m0, s56, 0x2000
	s_add_u32 s34, s34, 0x44000
	v_lshl_add_u64 v[238:239], s[52:53], 0, v[0:1]
	s_addc_u32 s35, s35, 0
	s_add_i32 s52, vcc_hi, s58
	global_load_lds_dwordx4 v[238:239], off
	v_lshl_add_u64 v[238:239], s[34:35], 0, v[174:175]
	s_mov_b32 m0, s52
	v_lshl_add_u64 v[198:199], v[198:199], 0, s[14:15]
	global_load_lds_dwordx4 v[238:239], off
	v_lshl_add_u64 v[238:239], s[34:35], 0, v[0:1]
	s_add_i32 m0, s52, 0x2000
	s_nop 0
	global_load_lds_dwordx4 v[238:239], off
	s_mov_b32 m0, s71
	s_nop 0
	global_load_lds_dwordx4 v[198:199], off
	v_lshl_add_u64 v[198:199], v[236:237], 0, s[14:15]
	s_mov_b32 m0, s76
	s_nop 0
	global_load_lds_dwordx4 v[198:199], off
	s_waitcnt vmcnt(8)
	s_waitcnt lgkmcnt(0)
	s_barrier
	v_mfma_f32_16x16x32_bf16 v[64:67], v[116:119], v[190:193], v[64:67]
	v_mfma_f32_16x16x32_bf16 v[64:67], v[120:123], v[194:197], v[64:67]
	v_mfma_f32_16x16x32_bf16 v[60:63], v[124:127], v[190:193], v[60:63]
	v_mfma_f32_16x16x32_bf16 v[60:63], v[136:139], v[194:197], v[60:63]
	v_mfma_f32_16x16x32_bf16 v[44:47], v[124:127], v[204:207], v[44:47]
	v_mfma_f32_16x16x32_bf16 v[44:47], v[136:139], v[208:211], v[44:47]
	v_mfma_f32_16x16x32_bf16 v[48:51], v[116:119], v[204:207], v[48:51]
	v_mfma_f32_16x16x32_bf16 v[48:51], v[120:123], v[208:211], v[48:51]
	v_mfma_f32_16x16x32_bf16 v[32:35], v[116:119], v[212:215], v[32:35]
	v_mfma_f32_16x16x32_bf16 v[32:35], v[120:123], v[216:219], v[32:35]
	v_mfma_f32_16x16x32_bf16 v[28:31], v[124:127], v[212:215], v[28:31]
	v_mfma_f32_16x16x32_bf16 v[28:31], v[136:139], v[216:219], v[28:31]
	v_mfma_f32_16x16x32_bf16 v[12:15], v[124:127], v[228:231], v[12:15]
	v_mfma_f32_16x16x32_bf16 v[12:15], v[136:139], v[232:235], v[12:15]
	v_mfma_f32_16x16x32_bf16 v[16:19], v[116:119], v[228:231], v[16:19]
	v_mfma_f32_16x16x32_bf16 v[16:19], v[120:123], v[232:235], v[16:19]
	v_mfma_f32_16x16x32_bf16 v[56:59], v[148:151], v[190:193], v[56:59]
	v_mfma_f32_16x16x32_bf16 v[56:59], v[152:155], v[194:197], v[56:59]
	v_mfma_f32_16x16x32_bf16 v[52:55], v[182:185], v[190:193], v[52:55]
	v_mfma_f32_16x16x32_bf16 v[52:55], v[186:189], v[194:197], v[52:55]
	v_mfma_f32_16x16x32_bf16 v[36:39], v[182:185], v[204:207], v[36:39]
	v_mfma_f32_16x16x32_bf16 v[36:39], v[186:189], v[208:211], v[36:39]
	v_mfma_f32_16x16x32_bf16 v[40:43], v[148:151], v[204:207], v[40:43]
	v_mfma_f32_16x16x32_bf16 v[40:43], v[152:155], v[208:211], v[40:43]
	v_mfma_f32_16x16x32_bf16 v[24:27], v[148:151], v[212:215], v[24:27]
	v_mfma_f32_16x16x32_bf16 v[24:27], v[152:155], v[216:219], v[24:27]
	v_mfma_f32_16x16x32_bf16 v[20:23], v[182:185], v[212:215], v[20:23]
	v_mfma_f32_16x16x32_bf16 v[20:23], v[186:189], v[216:219], v[20:23]
	v_mfma_f32_16x16x32_bf16 v[4:7], v[182:185], v[228:231], v[4:7]
	v_mfma_f32_16x16x32_bf16 v[4:7], v[186:189], v[232:235], v[4:7]
	v_mfma_f32_16x16x32_bf16 v[8:11], v[148:151], v[228:231], v[8:11]
	v_mfma_f32_16x16x32_bf16 v[8:11], v[152:155], v[232:235], v[8:11]
	s_barrier
	s_add_u32 s49, s49, 0x80000
	s_addc_u32 s97, s97, 0
	s_add_u32 s42, s42, 0x100
	s_addc_u32 s43, s43, 0
	s_cmp_ge_u32 vcc_lo, s69
	s_mov_b32 s34, vcc_lo
	s_cbranch_scc0 .LBB0_559
	s_setprio 0
	s_and_b64 vcc, exec, s[46:47]
	s_cbranch_vccz .LBB0_562
	s_barrier
